# same-XCD group barrier: L1 invalidate issued right after the arrival atomic (before the spin) so it overlaps the wait; on top of mixing wait fixes
# speedup vs baseline: 1.0038x; 1.0038x over previous
.LBB0_936:
	s_or_b64 exec, exec, s[10:11]
	buffer_inv sc1
	s_mov_b32 s12, 0x400001
	s_branch .LBB0_938

.LBB0_938:
	global_load_dword v0, v181, s[28:29] sc1
	s_mov_b64 s[10:11], -1
	s_waitcnt vmcnt(0)
	v_cmp_le_u32_e32 vcc, s14, v0
	s_cbranch_vccnz .LBB0_937
	s_sleep 1
	global_load_dword v0, v181, s[28:29] sc1
	s_waitcnt vmcnt(0)
	v_cmp_gt_u32_e32 vcc, s14, v0
	s_cbranch_vccz .LBB0_937
	s_sleep 1
	global_load_dword v0, v181, s[28:29] sc1
	s_waitcnt vmcnt(0)
	v_cmp_gt_u32_e32 vcc, s14, v0
	s_cbranch_vccz .LBB0_937
	s_sleep 1
	global_load_dword v0, v181, s[28:29] sc1
	s_waitcnt vmcnt(0)
	v_cmp_gt_u32_e32 vcc, s14, v0
	s_cbranch_vccz .LBB0_937
	s_sleep 1
	global_load_dword v0, v181, s[28:29] sc1
	s_waitcnt vmcnt(0)
	v_cmp_gt_u32_e32 vcc, s14, v0
	s_cbranch_vccz .LBB0_937
	s_add_i32 s12, s12, -5
	s_cmp_eq_u32 s12, 0
	s_cselect_b64 s[10:11], -1, 0
	s_sleep 1
	s_branch .LBB0_937
.LBB0_944:
	s_waitcnt vmcnt(0)
.LBB0_945:
	s_or_b64 exec, exec, s[8:9]
	s_movk_i32 s1, 0xb1
	s_mov_b64 s[8:9], 0
	s_barrier
	s_branch .LBB0_947
